# union + SwiGLU denominator as fma(e, 1/rs2, 1/rs2): one packed multiply fewer per output pair (f32 math, same operands)
# speedup vs baseline: 1.0077x; 1.0077x over previous
.LBB0_900:
	s_waitcnt lgkmcnt(0)
	v_lshl_or_b32 v136, s35, 7, v173
	v_ashrrev_i32_e32 v137, 31, v136
	v_lshl_add_u64 v[136:137], v[136:137], 1, s[66:67]
	v_mul_f32_e32 v188, 0xbfb8aa3b, v172
	v_mul_f32_e32 v190, v172, v172
	v_rcp_f32_e32 v198, v190
	v_pk_mul_f32 v[200:201], v[130:131], v[188:189] op_sel_hi:[1,0]
	v_pk_mul_f32 v[202:203], v[132:133], v[188:189] op_sel_hi:[1,0]
	v_pk_mul_f32 v[204:205], v[122:123], v[188:189] op_sel_hi:[1,0]
	v_pk_mul_f32 v[206:207], v[124:125], v[188:189] op_sel_hi:[1,0]
	v_exp_f32_e32 v200, v200
	v_exp_f32_e32 v201, v201
	v_exp_f32_e32 v202, v202
	v_exp_f32_e32 v203, v203
	v_exp_f32_e32 v204, v204
	v_exp_f32_e32 v205, v205
	v_exp_f32_e32 v206, v206
	v_exp_f32_e32 v207, v207
	v_pk_mul_f32 v[130:131], v[130:131], v[126:127]
	v_pk_mul_f32 v[132:133], v[132:133], v[128:129]
	v_pk_mul_f32 v[122:123], v[122:123], v[118:119]
	v_pk_mul_f32 v[124:125], v[124:125], v[120:121]
	v_fma_f32 v200, v200, v198, v198
	v_fma_f32 v201, v201, v198, v198
	v_fma_f32 v202, v202, v198, v198
	v_fma_f32 v203, v203, v198, v198
	v_fma_f32 v204, v204, v198, v198
	v_fma_f32 v205, v205, v198, v198
	v_fma_f32 v206, v206, v198, v198
	v_fma_f32 v207, v207, v198, v198
	v_rcp_f32_e32 v200, v200
	v_rcp_f32_e32 v201, v201
	v_rcp_f32_e32 v202, v202
	v_rcp_f32_e32 v203, v203
	v_rcp_f32_e32 v204, v204
	v_rcp_f32_e32 v205, v205
	v_rcp_f32_e32 v206, v206
	v_rcp_f32_e32 v207, v207
	v_mad_u64_u32 v[196:197], s[2:3], v162, s78, v[136:137]
	v_pk_mul_f32 v[130:131], v[130:131], v[200:201]
	v_pk_mul_f32 v[132:133], v[132:133], v[202:203]
	v_pk_mul_f32 v[122:123], v[122:123], v[204:205]
	v_pk_mul_f32 v[124:125], v[124:125], v[206:207]
	v_cvt_pk_bf16_f32 v192, v130, v131
	v_cvt_pk_bf16_f32 v193, v132, v133
	v_cvt_pk_bf16_f32 v194, v122, v123
	v_cvt_pk_bf16_f32 v195, v124, v125
	global_store_dwordx4 v[196:197], v[192:195], off
	v_mul_f32_e32 v188, 0xbfb8aa3b, v170
	v_mul_f32_e32 v190, v170, v170
	v_rcp_f32_e32 v198, v190
	v_pk_mul_f32 v[200:201], v[114:115], v[188:189] op_sel_hi:[1,0]
	v_pk_mul_f32 v[202:203], v[116:117], v[188:189] op_sel_hi:[1,0]
	v_pk_mul_f32 v[204:205], v[106:107], v[188:189] op_sel_hi:[1,0]
	v_pk_mul_f32 v[206:207], v[108:109], v[188:189] op_sel_hi:[1,0]
	v_exp_f32_e32 v200, v200
	v_exp_f32_e32 v201, v201
	v_exp_f32_e32 v202, v202
	v_exp_f32_e32 v203, v203
	v_exp_f32_e32 v204, v204
	v_exp_f32_e32 v205, v205
	v_exp_f32_e32 v206, v206
	v_exp_f32_e32 v207, v207
	v_pk_mul_f32 v[114:115], v[114:115], v[110:111]
	v_pk_mul_f32 v[116:117], v[116:117], v[112:113]
	v_pk_mul_f32 v[106:107], v[106:107], v[102:103]
	v_pk_mul_f32 v[108:109], v[108:109], v[104:105]
	v_fma_f32 v200, v200, v198, v198
	v_fma_f32 v201, v201, v198, v198
	v_fma_f32 v202, v202, v198, v198
	v_fma_f32 v203, v203, v198, v198
	v_fma_f32 v204, v204, v198, v198
	v_fma_f32 v205, v205, v198, v198
	v_fma_f32 v206, v206, v198, v198
	v_fma_f32 v207, v207, v198, v198
	v_rcp_f32_e32 v200, v200
	v_rcp_f32_e32 v201, v201
	v_rcp_f32_e32 v202, v202
	v_rcp_f32_e32 v203, v203
	v_rcp_f32_e32 v204, v204
	v_rcp_f32_e32 v205, v205
	v_rcp_f32_e32 v206, v206
	v_rcp_f32_e32 v207, v207
	v_mad_u64_u32 v[196:197], s[2:3], v160, s78, v[136:137]
	v_pk_mul_f32 v[114:115], v[114:115], v[200:201]
	v_pk_mul_f32 v[116:117], v[116:117], v[202:203]
	v_pk_mul_f32 v[106:107], v[106:107], v[204:205]
	v_pk_mul_f32 v[108:109], v[108:109], v[206:207]
	v_cvt_pk_bf16_f32 v192, v114, v115
	v_cvt_pk_bf16_f32 v193, v116, v117
	v_cvt_pk_bf16_f32 v194, v106, v107
	v_cvt_pk_bf16_f32 v195, v108, v109
	global_store_dwordx4 v[196:197], v[192:195], off
	v_mul_f32_e32 v188, 0xbfb8aa3b, v168
	v_mul_f32_e32 v190, v168, v168
	v_rcp_f32_e32 v198, v190
	v_pk_mul_f32 v[200:201], v[98:99], v[188:189] op_sel_hi:[1,0]
	v_pk_mul_f32 v[202:203], v[100:101], v[188:189] op_sel_hi:[1,0]
	v_pk_mul_f32 v[204:205], v[90:91], v[188:189] op_sel_hi:[1,0]
	v_pk_mul_f32 v[206:207], v[92:93], v[188:189] op_sel_hi:[1,0]
	v_exp_f32_e32 v200, v200
	v_exp_f32_e32 v201, v201
	v_exp_f32_e32 v202, v202
	v_exp_f32_e32 v203, v203
	v_exp_f32_e32 v204, v204
	v_exp_f32_e32 v205, v205
	v_exp_f32_e32 v206, v206
	v_exp_f32_e32 v207, v207
	v_pk_mul_f32 v[98:99], v[98:99], v[94:95]
	v_pk_mul_f32 v[100:101], v[100:101], v[96:97]
	v_pk_mul_f32 v[90:91], v[90:91], v[86:87]
	v_pk_mul_f32 v[92:93], v[92:93], v[88:89]
	v_fma_f32 v200, v200, v198, v198
	v_fma_f32 v201, v201, v198, v198
	v_fma_f32 v202, v202, v198, v198
	v_fma_f32 v203, v203, v198, v198
	v_fma_f32 v204, v204, v198, v198
	v_fma_f32 v205, v205, v198, v198
	v_fma_f32 v206, v206, v198, v198
	v_fma_f32 v207, v207, v198, v198
	v_rcp_f32_e32 v200, v200
	v_rcp_f32_e32 v201, v201
	v_rcp_f32_e32 v202, v202
	v_rcp_f32_e32 v203, v203
	v_rcp_f32_e32 v204, v204
	v_rcp_f32_e32 v205, v205
	v_rcp_f32_e32 v206, v206
	v_rcp_f32_e32 v207, v207
	v_mad_u64_u32 v[196:197], s[2:3], v158, s78, v[136:137]
	v_pk_mul_f32 v[98:99], v[98:99], v[200:201]
	v_pk_mul_f32 v[100:101], v[100:101], v[202:203]
	v_pk_mul_f32 v[90:91], v[90:91], v[204:205]
	v_pk_mul_f32 v[92:93], v[92:93], v[206:207]
	v_cvt_pk_bf16_f32 v192, v98, v99
	v_cvt_pk_bf16_f32 v193, v100, v101
	v_cvt_pk_bf16_f32 v194, v90, v91
	v_cvt_pk_bf16_f32 v195, v92, v93
	global_store_dwordx4 v[196:197], v[192:195], off
	v_mul_f32_e32 v188, 0xbfb8aa3b, v164
	v_mul_f32_e32 v190, v164, v164
	v_rcp_f32_e32 v198, v190
	v_pk_mul_f32 v[200:201], v[82:83], v[188:189] op_sel_hi:[1,0]
	v_pk_mul_f32 v[202:203], v[84:85], v[188:189] op_sel_hi:[1,0]
	v_pk_mul_f32 v[204:205], v[74:75], v[188:189] op_sel_hi:[1,0]
	v_pk_mul_f32 v[206:207], v[76:77], v[188:189] op_sel_hi:[1,0]
	v_exp_f32_e32 v200, v200
	v_exp_f32_e32 v201, v201
	v_exp_f32_e32 v202, v202
	v_exp_f32_e32 v203, v203
	v_exp_f32_e32 v204, v204
	v_exp_f32_e32 v205, v205
	v_exp_f32_e32 v206, v206
	v_exp_f32_e32 v207, v207
	v_pk_mul_f32 v[82:83], v[82:83], v[78:79]
	v_pk_mul_f32 v[84:85], v[84:85], v[80:81]
	v_pk_mul_f32 v[74:75], v[74:75], v[70:71]
	v_pk_mul_f32 v[76:77], v[76:77], v[72:73]
	v_fma_f32 v200, v200, v198, v198
	v_fma_f32 v201, v201, v198, v198
	v_fma_f32 v202, v202, v198, v198
	v_fma_f32 v203, v203, v198, v198
	v_fma_f32 v204, v204, v198, v198
	v_fma_f32 v205, v205, v198, v198
	v_fma_f32 v206, v206, v198, v198
	v_fma_f32 v207, v207, v198, v198
	v_rcp_f32_e32 v200, v200
	v_rcp_f32_e32 v201, v201
	v_rcp_f32_e32 v202, v202
	v_rcp_f32_e32 v203, v203
	v_rcp_f32_e32 v204, v204
	v_rcp_f32_e32 v205, v205
	v_rcp_f32_e32 v206, v206
	v_rcp_f32_e32 v207, v207
	v_mad_u64_u32 v[196:197], s[2:3], v156, s78, v[136:137]
	v_pk_mul_f32 v[82:83], v[82:83], v[200:201]
	v_pk_mul_f32 v[84:85], v[84:85], v[202:203]
	v_pk_mul_f32 v[74:75], v[74:75], v[204:205]
	v_pk_mul_f32 v[76:77], v[76:77], v[206:207]
	v_cvt_pk_bf16_f32 v192, v82, v83
	v_cvt_pk_bf16_f32 v193, v84, v85
	v_cvt_pk_bf16_f32 v194, v74, v75
	v_cvt_pk_bf16_f32 v195, v76, v77
	global_store_dwordx4 v[196:197], v[192:195], off
	v_mul_f32_e32 v188, 0xbfb8aa3b, v166
	v_mul_f32_e32 v190, v166, v166
	v_rcp_f32_e32 v198, v190
	v_pk_mul_f32 v[200:201], v[66:67], v[188:189] op_sel_hi:[1,0]
	v_pk_mul_f32 v[202:203], v[68:69], v[188:189] op_sel_hi:[1,0]
	v_pk_mul_f32 v[204:205], v[58:59], v[188:189] op_sel_hi:[1,0]
	v_pk_mul_f32 v[206:207], v[60:61], v[188:189] op_sel_hi:[1,0]
	v_exp_f32_e32 v200, v200
	v_exp_f32_e32 v201, v201
	v_exp_f32_e32 v202, v202
	v_exp_f32_e32 v203, v203
	v_exp_f32_e32 v204, v204
	v_exp_f32_e32 v205, v205
	v_exp_f32_e32 v206, v206
	v_exp_f32_e32 v207, v207
	v_pk_mul_f32 v[66:67], v[66:67], v[62:63]
	v_pk_mul_f32 v[68:69], v[68:69], v[64:65]
	v_pk_mul_f32 v[58:59], v[58:59], v[54:55]
	v_pk_mul_f32 v[60:61], v[60:61], v[56:57]
	v_fma_f32 v200, v200, v198, v198
	v_fma_f32 v201, v201, v198, v198
	v_fma_f32 v202, v202, v198, v198
	v_fma_f32 v203, v203, v198, v198
	v_fma_f32 v204, v204, v198, v198
	v_fma_f32 v205, v205, v198, v198
	v_fma_f32 v206, v206, v198, v198
	v_fma_f32 v207, v207, v198, v198
	v_rcp_f32_e32 v200, v200
	v_rcp_f32_e32 v201, v201
	v_rcp_f32_e32 v202, v202
	v_rcp_f32_e32 v203, v203
	v_rcp_f32_e32 v204, v204
	v_rcp_f32_e32 v205, v205
	v_rcp_f32_e32 v206, v206
	v_rcp_f32_e32 v207, v207
	v_mad_u64_u32 v[196:197], s[2:3], v154, s78, v[136:137]
	v_pk_mul_f32 v[66:67], v[66:67], v[200:201]
	v_pk_mul_f32 v[68:69], v[68:69], v[202:203]
	v_pk_mul_f32 v[58:59], v[58:59], v[204:205]
	v_pk_mul_f32 v[60:61], v[60:61], v[206:207]
	v_cvt_pk_bf16_f32 v192, v66, v67
	v_cvt_pk_bf16_f32 v193, v68, v69
	v_cvt_pk_bf16_f32 v194, v58, v59
	v_cvt_pk_bf16_f32 v195, v60, v61
	global_store_dwordx4 v[196:197], v[192:195], off
	v_mul_f32_e32 v188, 0xbfb8aa3b, v174
	v_mul_f32_e32 v190, v174, v174
	v_rcp_f32_e32 v198, v190
	v_pk_mul_f32 v[200:201], v[50:51], v[188:189] op_sel_hi:[1,0]
	v_pk_mul_f32 v[202:203], v[52:53], v[188:189] op_sel_hi:[1,0]
	v_pk_mul_f32 v[204:205], v[42:43], v[188:189] op_sel_hi:[1,0]
	v_pk_mul_f32 v[206:207], v[44:45], v[188:189] op_sel_hi:[1,0]
	v_exp_f32_e32 v200, v200
	v_exp_f32_e32 v201, v201
	v_exp_f32_e32 v202, v202
	v_exp_f32_e32 v203, v203
	v_exp_f32_e32 v204, v204
	v_exp_f32_e32 v205, v205
	v_exp_f32_e32 v206, v206
	v_exp_f32_e32 v207, v207
	v_pk_mul_f32 v[50:51], v[50:51], v[46:47]
	v_pk_mul_f32 v[52:53], v[52:53], v[48:49]
	v_pk_mul_f32 v[42:43], v[42:43], v[38:39]
	v_pk_mul_f32 v[44:45], v[44:45], v[40:41]
	v_fma_f32 v200, v200, v198, v198
	v_fma_f32 v201, v201, v198, v198
	v_fma_f32 v202, v202, v198, v198
	v_fma_f32 v203, v203, v198, v198
	v_fma_f32 v204, v204, v198, v198
	v_fma_f32 v205, v205, v198, v198
	v_fma_f32 v206, v206, v198, v198
	v_fma_f32 v207, v207, v198, v198
	v_rcp_f32_e32 v200, v200
	v_rcp_f32_e32 v201, v201
	v_rcp_f32_e32 v202, v202
	v_rcp_f32_e32 v203, v203
	v_rcp_f32_e32 v204, v204
	v_rcp_f32_e32 v205, v205
	v_rcp_f32_e32 v206, v206
	v_rcp_f32_e32 v207, v207
	v_mad_u64_u32 v[196:197], s[2:3], v152, s78, v[136:137]
	v_pk_mul_f32 v[50:51], v[50:51], v[200:201]
	v_pk_mul_f32 v[52:53], v[52:53], v[202:203]
	v_pk_mul_f32 v[42:43], v[42:43], v[204:205]
	v_pk_mul_f32 v[44:45], v[44:45], v[206:207]
	v_cvt_pk_bf16_f32 v192, v50, v51
	v_cvt_pk_bf16_f32 v193, v52, v53
	v_cvt_pk_bf16_f32 v194, v42, v43
	v_cvt_pk_bf16_f32 v195, v44, v45
	global_store_dwordx4 v[196:197], v[192:195], off
	v_mul_f32_e32 v188, 0xbfb8aa3b, v182
	v_mul_f32_e32 v190, v182, v182
	v_rcp_f32_e32 v198, v190
	v_pk_mul_f32 v[200:201], v[34:35], v[188:189] op_sel_hi:[1,0]
	v_pk_mul_f32 v[202:203], v[36:37], v[188:189] op_sel_hi:[1,0]
	v_pk_mul_f32 v[204:205], v[26:27], v[188:189] op_sel_hi:[1,0]
	v_pk_mul_f32 v[206:207], v[28:29], v[188:189] op_sel_hi:[1,0]
	v_exp_f32_e32 v200, v200
	v_exp_f32_e32 v201, v201
	v_exp_f32_e32 v202, v202
	v_exp_f32_e32 v203, v203
	v_exp_f32_e32 v204, v204
	v_exp_f32_e32 v205, v205
	v_exp_f32_e32 v206, v206
	v_exp_f32_e32 v207, v207
	v_pk_mul_f32 v[34:35], v[34:35], v[30:31]
	v_pk_mul_f32 v[36:37], v[36:37], v[32:33]
	v_pk_mul_f32 v[26:27], v[26:27], v[22:23]
	v_pk_mul_f32 v[28:29], v[28:29], v[24:25]
	v_fma_f32 v200, v200, v198, v198
	v_fma_f32 v201, v201, v198, v198
	v_fma_f32 v202, v202, v198, v198
	v_fma_f32 v203, v203, v198, v198
	v_fma_f32 v204, v204, v198, v198
	v_fma_f32 v205, v205, v198, v198
	v_fma_f32 v206, v206, v198, v198
	v_fma_f32 v207, v207, v198, v198
	v_rcp_f32_e32 v200, v200
	v_rcp_f32_e32 v201, v201
	v_rcp_f32_e32 v202, v202
	v_rcp_f32_e32 v203, v203
	v_rcp_f32_e32 v204, v204
	v_rcp_f32_e32 v205, v205
	v_rcp_f32_e32 v206, v206
	v_rcp_f32_e32 v207, v207
	v_mad_u64_u32 v[196:197], s[2:3], v150, s78, v[136:137]
	v_pk_mul_f32 v[34:35], v[34:35], v[200:201]
	v_pk_mul_f32 v[36:37], v[36:37], v[202:203]
	v_pk_mul_f32 v[26:27], v[26:27], v[204:205]
	v_pk_mul_f32 v[28:29], v[28:29], v[206:207]
	v_cvt_pk_bf16_f32 v192, v34, v35
	v_cvt_pk_bf16_f32 v193, v36, v37
	v_cvt_pk_bf16_f32 v194, v26, v27
	v_cvt_pk_bf16_f32 v195, v28, v29
	global_store_dwordx4 v[196:197], v[192:195], off
	v_mul_f32_e32 v188, 0xbfb8aa3b, v134
	v_mul_f32_e32 v190, v134, v134
	v_rcp_f32_e32 v198, v190
	v_pk_mul_f32 v[200:201], v[18:19], v[188:189] op_sel_hi:[1,0]
	v_pk_mul_f32 v[202:203], v[20:21], v[188:189] op_sel_hi:[1,0]
	v_pk_mul_f32 v[204:205], v[6:7], v[188:189] op_sel_hi:[1,0]
	v_pk_mul_f32 v[206:207], v[8:9], v[188:189] op_sel_hi:[1,0]
	v_exp_f32_e32 v200, v200
	v_exp_f32_e32 v201, v201
	v_exp_f32_e32 v202, v202
	v_exp_f32_e32 v203, v203
	v_exp_f32_e32 v204, v204
	v_exp_f32_e32 v205, v205
	v_exp_f32_e32 v206, v206
	v_exp_f32_e32 v207, v207
	v_pk_mul_f32 v[18:19], v[18:19], v[10:11]
	v_pk_mul_f32 v[20:21], v[20:21], v[12:13]
	v_pk_mul_f32 v[6:7], v[6:7], v[2:3]
	v_pk_mul_f32 v[8:9], v[8:9], v[4:5]
	v_fma_f32 v200, v200, v198, v198
	v_fma_f32 v201, v201, v198, v198
	v_fma_f32 v202, v202, v198, v198
	v_fma_f32 v203, v203, v198, v198
	v_fma_f32 v204, v204, v198, v198
	v_fma_f32 v205, v205, v198, v198
	v_fma_f32 v206, v206, v198, v198
	v_fma_f32 v207, v207, v198, v198
	v_rcp_f32_e32 v200, v200
	v_rcp_f32_e32 v201, v201
	v_rcp_f32_e32 v202, v202
	v_rcp_f32_e32 v203, v203
	v_rcp_f32_e32 v204, v204
	v_rcp_f32_e32 v205, v205
	v_rcp_f32_e32 v206, v206
	v_rcp_f32_e32 v207, v207
	v_mad_u64_u32 v[196:197], s[2:3], v148, s78, v[136:137]
	v_pk_mul_f32 v[18:19], v[18:19], v[200:201]
	v_pk_mul_f32 v[20:21], v[20:21], v[202:203]
	v_pk_mul_f32 v[6:7], v[6:7], v[204:205]
	v_pk_mul_f32 v[8:9], v[8:9], v[206:207]
	v_cvt_pk_bf16_f32 v192, v18, v19
	v_cvt_pk_bf16_f32 v193, v20, v21
	v_cvt_pk_bf16_f32 v194, v6, v7
	v_cvt_pk_bf16_f32 v195, v8, v9
	global_store_dwordx4 v[196:197], v[192:195], off
	s_mov_b64 s[4:5], -1
	s_andn2_b64 vcc, exec, s[0:1]
	s_cbranch_vccnz .LBB0_889
	s_andn2_b64 vcc, exec, s[6:7]
	s_cbranch_vccnz .LBB0_888
	s_barrier
	s_branch .LBB0_888
